# stack + routing phase: a unit's twelve operand loads issued one unit ahead (behind the previous unit's second barrier), overlapping the list-slot atomic
# speedup vs baseline: 1.0060x; 1.0060x over previous
.LBB0_218:
	s_or_b64 exec, exec, s[0:1]
	s_add_u32 s90, s20, 0x1f100000
	s_addc_u32 s91, s21, 0
	s_add_u32 s92, s18, 0x4000000
	s_addc_u32 s93, s19, 0
	v_readlane_b32 s0, v251, 36
	s_cmpk_lt_i32 s0, 0x800
	s_cselect_b64 s[2:3], -1, 0
	v_writelane_b32 v251, s2, 37
	s_cmpk_gt_i32 s0, 0x7ff
	s_waitcnt lgkmcnt(0)
	s_barrier
	v_writelane_b32 v251, s3, 38
	s_cbranch_scc1 .LBB0_247
	v_ashrrev_i32_e32 v0, 5, v168
	v_lshlrev_b32_e32 v16, 3, v0
	v_lshlrev_b32_e32 v29, 2, v0
	v_mbcnt_lo_u32_b32 v0, -1, 0
	v_mbcnt_hi_u32_b32 v0, -1, v0
	v_and_b32_e32 v3, 64, v0
	v_xor_b32_e32 v2, 32, v0
	v_add_u32_e32 v3, 64, v3
	v_lshlrev_b32_e32 v1, 2, v170
	s_add_i32 s2, 0, 0x23c00
	v_cmp_lt_i32_e32 vcc, v2, v3
	v_and_b32_e32 v26, 31, v168
	v_add_u32_e32 v27, s2, v1
	v_ashrrev_i32_e32 v17, 31, v16
	v_cndmask_b32_e32 v0, v0, v2, vcc
	v_ashrrev_i32_e32 v171, 31, v170
	s_add_i32 s2, 0, 0x23c80
	v_cmp_gt_i32_e64 s[0:1], 32, v170
	s_mov_b32 s3, 0
	v_lshl_or_b32 v28, s89, 5, v26
	v_lshl_add_u64 v[18:19], v[16:17], 2, s[70:71]
	v_lshlrev_b32_e32 v30, 2, v0
	v_cmp_gt_u32_e64 s[6:7], 32, v168
	v_lshl_add_u64 v[20:21], v[170:171], 2, s[20:21]
	v_add_u32_e32 v31, s2, v1
	v_or_b32_e32 v32, 1, v29
	v_or_b32_e32 v33, 2, v29
	v_or_b32_e32 v34, 3, v29
	v_add_u32_e32 v35, 8, v29
	v_add_u32_e32 v36, 9, v29
	v_add_u32_e32 v37, 10, v29
	v_add_u32_e32 v38, 11, v29
	v_add_u32_e32 v39, 16, v29
	v_add_u32_e32 v40, 17, v29
	v_add_u32_e32 v41, 18, v29
	v_add_u32_e32 v42, 19, v29
	v_add_u32_e32 v43, 24, v29
	v_add_u32_e32 v44, 25, v29
	v_add_u32_e32 v45, 26, v29
	v_add_u32_e32 v46, 27, v29
	v_mov_b32_e32 v23, 0
	v_mov_b32_e32 v47, 0xff61b1e0
	v_mov_b32_e32 v48, 1
	v_mov_b32_e32 v49, 0xff800000
	v_readlane_b32 s28, v251, 36
	s_mov_b32 s98, s28
	s_bfe_u32 s99, s98, 0x50004
	s_ashr_i32 s100, s98, 9
	s_and_b32 s101, s98, 15
	v_lshl_add_u32 v130, s99, 8, v28
	v_lshl_add_u32 v130, s100, 13, v130
	s_lshl_b32 s100, s100, 4
	s_or_b32 s100, s100, s101
	s_lshl_b32 s100, s100, 5
	v_or_b32_e32 v128, s100, v26
	v_ashrrev_i32_e32 v129, 31, v128
	v_lshlrev_b64 v[128:129], 8, v[128:129]
	v_lshl_add_u64 v[128:129], v[18:19], 0, v[128:129]
	v_ashrrev_i32_e32 v131, 31, v130
	v_lshlrev_b64 v[130:131], 11, v[130:131]
	v_lshl_add_u64 v[130:131], s[24:25], 0, v[130:131]
	s_lshl_b32 s100, s101, 7
	s_mov_b32 s101, 0
	v_lshl_add_u64 v[130:131], v[130:131], 0, s[100:101]
	v_lshl_add_u64 v[130:131], v[16:17], 1, v[130:131]
	global_load_dwordx4 v[116:119], v[128:129], off offset:16
	global_load_dwordx4 v[120:123], v[128:129], off
	global_load_dwordx4 v[52:55], v[128:129], off offset:64
	global_load_dwordx4 v[124:127], v[130:131], off
	global_load_dwordx4 v[56:59], v[128:129], off offset:80
	global_load_dwordx4 v[60:63], v[128:129], off offset:128
	global_load_dwordx4 v[64:67], v[130:131], off offset:32
	global_load_dwordx4 v[68:71], v[128:129], off offset:144
	global_load_dwordx4 v[72:75], v[128:129], off offset:192
	global_load_dwordx4 v[76:79], v[130:131], off offset:64
	global_load_dwordx4 v[80:83], v[128:129], off offset:208
	global_load_dwordx4 v[84:87], v[130:131], off offset:96
	s_branch .LBB0_221

.LBB0_221:
	s_and_saveexec_b64 s[8:9], s[0:1]
	ds_write_b32 v27, v23
	s_or_b64 exec, exec, s[8:9]
	s_bfe_u32 s29, s28, 0x50004
	s_ashr_i32 s2, s28, 9
	v_lshl_add_u32 v50, s29, 8, v28
	s_and_b32 s9, s28, 15
	v_lshl_add_u32 v24, s2, 13, v50
	s_lshl_b32 s2, s2, 4
	s_or_b32 s30, s2, s9
	s_lshl_b32 s8, s30, 5
	v_or_b32_e32 v0, s8, v26
	v_ashrrev_i32_e32 v1, 31, v0
	v_lshlrev_b64 v[0:1], 8, v[0:1]
	v_lshl_add_u64 v[12:13], v[18:19], 0, v[0:1]
	s_waitcnt lgkmcnt(0)
	s_barrier
	v_ashrrev_i32_e32 v25, 31, v24
	v_lshlrev_b64 v[8:9], 11, v[24:25]
	v_lshl_add_u64 v[8:9], s[24:25], 0, v[8:9]
	s_lshl_b32 s2, s9, 7
	v_lshl_add_u64 v[8:9], v[8:9], 0, s[2:3]
	v_lshl_add_u64 v[14:15], v[16:17], 1, v[8:9]
	v_cmp_gt_i32_e32 vcc, s29, v29
	s_waitcnt vmcnt(9)
	v_cvt_pk_bf16_f32 v52, v52, v53
	v_cvt_pk_bf16_f32 v53, v54, v55
	v_cvt_pk_bf16_f32 v4, v120, v121
	v_cvt_pk_bf16_f32 v5, v122, v123
	v_cvt_pk_bf16_f32 v6, v116, v117
	v_cvt_pk_bf16_f32 v7, v118, v119
	s_waitcnt vmcnt(7)
	v_cvt_pk_bf16_f32 v54, v56, v57
	v_cvt_pk_bf16_f32 v55, v58, v59
	v_mfma_f32_32x32x16_bf16 v[0:15], v[4:7], v[124:127], 0
	s_waitcnt vmcnt(6)
	v_cvt_pk_bf16_f32 v56, v60, v61
	v_cvt_pk_bf16_f32 v57, v62, v63
	s_waitcnt vmcnt(4)
	v_cvt_pk_bf16_f32 v58, v68, v69
	v_cvt_pk_bf16_f32 v59, v70, v71
	v_mfma_f32_32x32x16_bf16 v[0:15], v[52:55], v[64:67], v[0:15]
	s_waitcnt vmcnt(3)
	v_cvt_pk_bf16_f32 v52, v72, v73
	v_cvt_pk_bf16_f32 v53, v74, v75
	s_waitcnt vmcnt(1)
	v_cvt_pk_bf16_f32 v54, v80, v81
	v_cvt_pk_bf16_f32 v55, v82, v83
	v_mfma_f32_32x32x16_bf16 v[0:15], v[56:59], v[76:79], v[0:15]
	s_waitcnt vmcnt(0)
	v_mfma_f32_32x32x16_bf16 v[0:15], v[52:55], v[84:87], v[0:15]
	s_nop 11
	v_and_b32_e32 v0, 0xffffffe0, v0
	v_and_b32_e32 v1, 0xffffffe0, v1
	v_cndmask_b32_e32 v0, v47, v0, vcc
	v_cmp_gt_i32_e32 vcc, s29, v32
	v_and_b32_e32 v2, 0xffffffe0, v2
	v_or_b32_e32 v0, v0, v29
	v_cndmask_b32_e32 v1, v47, v1, vcc
	v_cmp_gt_i32_e32 vcc, s29, v33
	v_and_b32_e32 v3, 0xffffffe0, v3
	v_or_b32_e32 v1, v1, v32
	v_cndmask_b32_e32 v2, v47, v2, vcc
	v_cmp_gt_i32_e32 vcc, s29, v34
	v_max_f32_e32 v0, v0, v0
	v_and_b32_e32 v4, 0xffffffe0, v4
	v_cndmask_b32_e32 v3, v47, v3, vcc
	v_cmp_gt_i32_e32 vcc, s29, v35
	v_or_b32_e32 v2, v2, v33
	v_max_f32_e32 v1, v1, v1
	v_max_f32_e32 v22, 0xff61b1e6, v0
	v_min_f32_e32 v0, 0xff61b1e6, v0
	v_and_b32_e32 v5, 0xffffffe0, v5
	v_cndmask_b32_e32 v4, v47, v4, vcc
	v_cmp_gt_i32_e32 vcc, s29, v36
	v_or_b32_e32 v3, v3, v34
	v_max_f32_e32 v2, v2, v2
	v_max_f32_e32 v0, 0xff61b1e6, v0
	v_max_f32_e32 v51, v22, v1
	v_min_f32_e32 v1, v22, v1
	v_and_b32_e32 v6, 0xffffffe0, v6
	v_cndmask_b32_e32 v5, v47, v5, vcc
	v_cmp_gt_i32_e32 vcc, s29, v37
	v_or_b32_e32 v4, v4, v35
	v_max_f32_e32 v3, v3, v3
	v_max_f32_e32 v22, v0, v1
	v_min_f32_e32 v1, v0, v1
	v_max_f32_e32 v52, v51, v2
	v_min_f32_e32 v2, v51, v2
	v_and_b32_e32 v7, 0xffffffe0, v7
	v_cndmask_b32_e32 v6, v47, v6, vcc
	v_cmp_gt_i32_e32 vcc, s29, v38
	v_or_b32_e32 v5, v5, v36
	v_max_f32_e32 v4, v4, v4
	v_max_f32_e32 v0, v0, v1
	v_max_f32_e32 v1, v22, v2
	v_min_f32_e32 v2, v22, v2
	v_max_f32_e32 v22, v52, v3
	v_min_f32_e32 v3, v52, v3
	v_and_b32_e32 v8, 0xffffffe0, v8
	v_cndmask_b32_e32 v7, v47, v7, vcc
	v_cmp_gt_i32_e32 vcc, s29, v39
	v_or_b32_e32 v6, v6, v37
	v_max_f32_e32 v5, v5, v5
	v_max_f32_e32 v51, v1, v3
	v_min_f32_e32 v1, v1, v3
	v_max_f32_e32 v3, v22, v4
	v_min_f32_e32 v4, v22, v4
	v_cndmask_b32_e32 v8, v47, v8, vcc
	v_or_b32_e32 v7, v7, v38
	v_max_f32_e32 v6, v6, v6
	v_max3_f32 v0, v0, v2, v1
	v_max_f32_e32 v1, v51, v4
	v_min_f32_e32 v2, v51, v4
	v_max_f32_e32 v4, v3, v5
	v_min_f32_e32 v3, v3, v5
	v_or_b32_e32 v8, v8, v39
	v_max_f32_e32 v7, v7, v7
	v_max_f32_e32 v5, v1, v3
	v_min_f32_e32 v1, v1, v3
	v_max_f32_e32 v3, v4, v6
	v_min_f32_e32 v4, v4, v6
	v_max_f32_e32 v8, v8, v8
	v_max3_f32 v0, v0, v2, v1
	v_max_f32_e32 v1, v5, v4
	v_min_f32_e32 v2, v5, v4
	v_max_f32_e32 v4, v3, v7
	v_min_f32_e32 v3, v3, v7
	v_and_b32_e32 v9, 0xffffffe0, v9
	v_max_f32_e32 v5, v1, v3
	v_min_f32_e32 v1, v1, v3
	v_max_f32_e32 v3, v4, v8
	v_min_f32_e32 v4, v4, v8
	v_cmp_gt_i32_e32 vcc, s29, v40
	v_max3_f32 v0, v0, v2, v1
	v_max_f32_e32 v1, v5, v4
	v_min_f32_e32 v2, v5, v4
	v_cndmask_b32_e32 v4, v47, v9, vcc
	v_or_b32_e32 v4, v4, v40
	v_max_f32_e32 v4, v4, v4
	v_max_f32_e32 v5, v3, v4
	v_min_f32_e32 v3, v3, v4
	v_max_f32_e32 v4, v1, v3
	v_min_f32_e32 v1, v1, v3
	v_max3_f32 v0, v0, v2, v1
	v_and_b32_e32 v1, 0xffffffe0, v10
	v_cmp_gt_i32_e32 vcc, s29, v41
	s_nop 1
	v_cndmask_b32_e32 v1, v47, v1, vcc
	v_or_b32_e32 v1, v1, v41
	v_max_f32_e32 v1, v1, v1
	v_max_f32_e32 v2, v5, v1
	v_min_f32_e32 v1, v5, v1
	v_max_f32_e32 v3, v4, v1
	v_min_f32_e32 v1, v4, v1
	v_and_b32_e32 v4, 0xffffffe0, v11
	v_cmp_gt_i32_e32 vcc, s29, v42
	s_nop 1
	v_cndmask_b32_e32 v4, v47, v4, vcc
	v_or_b32_e32 v4, v4, v42
	v_max_f32_e32 v4, v4, v4
	v_max_f32_e32 v5, v2, v4
	v_min_f32_e32 v2, v2, v4
	v_max_f32_e32 v4, v3, v2
	v_min_f32_e32 v2, v3, v2
	v_max3_f32 v0, v0, v1, v2
	v_and_b32_e32 v1, 0xffffffe0, v12
	v_cmp_gt_i32_e32 vcc, s29, v43
	s_nop 1
	v_cndmask_b32_e32 v1, v47, v1, vcc
	v_or_b32_e32 v1, v1, v43
	v_max_f32_e32 v1, v1, v1
	v_max_f32_e32 v2, v5, v1
	v_min_f32_e32 v1, v5, v1
	v_max_f32_e32 v3, v4, v1
	v_min_f32_e32 v1, v4, v1
	v_and_b32_e32 v4, 0xffffffe0, v13
	v_cmp_gt_i32_e32 vcc, s29, v44
	s_nop 1
	v_cndmask_b32_e32 v4, v47, v4, vcc
	v_or_b32_e32 v4, v4, v44
	v_max_f32_e32 v4, v4, v4
	v_max_f32_e32 v5, v2, v4
	v_min_f32_e32 v2, v2, v4
	v_max_f32_e32 v4, v3, v2
	v_min_f32_e32 v2, v3, v2
	v_max3_f32 v0, v0, v1, v2
	v_and_b32_e32 v1, 0xffffffe0, v14
	v_cmp_gt_i32_e32 vcc, s29, v45
	s_nop 1
	v_cndmask_b32_e32 v1, v47, v1, vcc
	v_or_b32_e32 v1, v1, v45
	v_max_f32_e32 v1, v1, v1
	v_max_f32_e32 v2, v5, v1
	v_min_f32_e32 v1, v5, v1
	v_max_f32_e32 v3, v4, v1
	v_min_f32_e32 v1, v4, v1
	v_and_b32_e32 v4, 0xffffffe0, v15
	v_cmp_gt_i32_e32 vcc, s29, v46
	s_nop 1
	v_cndmask_b32_e32 v4, v47, v4, vcc
	v_or_b32_e32 v4, v4, v46
	v_max_f32_e32 v4, v4, v4
	v_max_f32_e32 v5, v2, v4
	v_min_f32_e32 v2, v2, v4
	ds_bpermute_b32 v6, v30, v5
	v_max_f32_e32 v4, v3, v2
	v_min_f32_e32 v2, v3, v2
	v_max3_f32 v0, v0, v1, v2
	ds_bpermute_b32 v1, v30, v4
	ds_bpermute_b32 v2, v30, v0
	s_waitcnt lgkmcnt(2)
	v_max_f32_e32 v3, v6, v6
	v_max_f32_e32 v6, v5, v3
	v_min_f32_e32 v3, v5, v3
	v_max_f32_e32 v5, v4, v3
	v_min_f32_e32 v3, v4, v3
	s_waitcnt lgkmcnt(1)
	v_max_f32_e32 v1, v1, v1
	v_max_f32_e32 v0, v0, v3
	v_max_f32_e32 v3, v6, v1
	v_min_f32_e32 v1, v6, v1
	s_waitcnt lgkmcnt(0)
	v_max_f32_e32 v2, v2, v2
	v_max_f32_e32 v4, v5, v1
	v_min_f32_e32 v1, v5, v1
	v_max_f32_e32 v5, v3, v2
	v_min_f32_e32 v2, v3, v2
	v_max_f32_e32 v3, v4, v2
	v_min_f32_e32 v2, v4, v2
	v_max3_f32 v0, v0, v1, v2
	v_and_b32_e32 v2, 31, v5
	v_and_b32_e32 v1, 31, v3
	v_and_b32_e32 v0, 31, v0
	v_mov_b32_e32 v3, 0
	v_mov_b32_e32 v4, 0
	v_mov_b32_e32 v5, 0
	s_and_saveexec_b64 s[10:11], s[6:7]
	s_cbranch_execz .LBB0_235
	s_cmp_eq_u32 s29, 0
	s_cbranch_scc1 .LBB0_246
	v_lshl_add_u32 v3, v2, 2, 0
	v_add_u32_e32 v3, 0x23c00, v3
	ds_add_rtn_u32 v3, v3, v48
	s_cbranch_execnz .LBB0_227

.LBB0_235:
	s_or_b64 exec, exec, s[10:11]
	s_waitcnt lgkmcnt(0)
	s_barrier
	s_add_i32 s98, s28, s22
	s_bfe_u32 s99, s98, 0x50004
	s_ashr_i32 s100, s98, 9
	s_and_b32 s101, s98, 15
	v_lshl_add_u32 v130, s99, 8, v28
	v_lshl_add_u32 v130, s100, 13, v130
	s_lshl_b32 s100, s100, 4
	s_or_b32 s100, s100, s101
	s_lshl_b32 s100, s100, 5
	v_or_b32_e32 v128, s100, v26
	v_ashrrev_i32_e32 v129, 31, v128
	v_lshlrev_b64 v[128:129], 8, v[128:129]
	v_lshl_add_u64 v[128:129], v[18:19], 0, v[128:129]
	v_ashrrev_i32_e32 v131, 31, v130
	v_lshlrev_b64 v[130:131], 11, v[130:131]
	v_lshl_add_u64 v[130:131], s[24:25], 0, v[130:131]
	s_lshl_b32 s100, s101, 7
	s_mov_b32 s101, 0
	v_lshl_add_u64 v[130:131], v[130:131], 0, s[100:101]
	v_lshl_add_u64 v[130:131], v[16:17], 1, v[130:131]
	global_load_dwordx4 v[116:119], v[128:129], off offset:16
	global_load_dwordx4 v[120:123], v[128:129], off
	global_load_dwordx4 v[52:55], v[128:129], off offset:64
	global_load_dwordx4 v[124:127], v[130:131], off
	global_load_dwordx4 v[56:59], v[128:129], off offset:80
	global_load_dwordx4 v[60:63], v[128:129], off offset:128
	global_load_dwordx4 v[64:67], v[130:131], off offset:32
	global_load_dwordx4 v[68:71], v[128:129], off offset:144
	global_load_dwordx4 v[72:75], v[128:129], off offset:192
	global_load_dwordx4 v[76:79], v[130:131], off offset:64
	global_load_dwordx4 v[80:83], v[128:129], off offset:208
	global_load_dwordx4 v[84:87], v[130:131], off offset:96
	s_and_saveexec_b64 s[10:11], s[0:1]
	s_cbranch_execz .LBB0_239
	ds_read_b32 v6, v27
	v_mov_b32_e32 v7, 0
	s_waitcnt lgkmcnt(0)
	v_cmp_ne_u32_e32 vcc, 0, v6
	s_and_saveexec_b64 s[26:27], vcc
	s_cbranch_execz .LBB0_238
	s_ashr_i32 s9, s8, 31
	v_lshl_add_u64 v[8:9], s[8:9], 2, v[20:21]
	global_atomic_add v7, v[8:9], v6, off sc0
